# loop-edge edit in the attention fast path: end-of-iteration LDS wait + barrier moved behind the next tile's address code and global loads (last-tile path takes them at entry)
# baseline (speedup 1.0000x reference)
; DI void attn_item(const Params& p, int l, int item, char* lds) {
;     ...
;     for (int kt = 0; kt < 2; ++kt) {
; #pragma unroll
;       for (int e = 0; e < 16; ++e) s[kt][e] = 0.f;
; #pragma unroll
;       for (int ks = 0; ks < 4; ++ks) {
;         const bf16x8 kf = *(const bf16x8*)(Ks + (m * 64 + kt * 32 + q) * ALD + ks * 16 + hh * 8);
;         s[kt] = __builtin_amdgcn_mfma_f32_32x32x16_bf16(kf, qf[ks], s[kt], 0, 0, 0);
;       }
;     }
;     float mx = -1e30f;
;     const float dbase = qposf - (float)(j * 64 + 4 * hh);
; #pragma unroll
;     for (int kt = 0; kt < 2; ++kt)
; #pragma unroll
;       for (int e = 0; e < 16; ++e) {
;         const float dd = dbase - (float)(kt * 32 + (e & 3) + 8 * (e >> 2));
;         const float v = s[kt][e] * c1 - sl2 * fabsf(dd);
;         s[kt][e] = v; mx = fmaxf(mx, v);
;       }
;     mx = fmaxf(mx, __shfl_xor(mx, 32));
;     const float mnew = fmaxf(mrun, mx);
;     const float alpha = __builtin_amdgcn_exp2f(mrun - mnew);
;     const bool resc = mnew > mrun;
;     mrun = mnew;
;     float ps = 0.f;
; #pragma unroll
;     for (int kt = 0; kt < 2; ++kt)
; #pragma unroll
;       for (int e = 0; e < 16; ++e) { const float pe = __builtin_amdgcn_exp2f(s[kt][e] - mnew); s[kt][e] = pe; ps += pe; }
;     lrun = lrun * alpha + ps;
;     if (__any(resc)) {
; #pragma unroll
;       for (int i = 0; i < 4; ++i)
; #pragma unroll
;         for (int e = 0; e < 16; ++e) O[i][e] *= alpha;
;     ...
;     __syncthreads();
;     if (j + 1 < nch) sstore();
;     __syncthreads();
.Lfa_body:
	s_waitcnt lgkmcnt(0)
	s_barrier
	ds_read_b128 v[2:5], v202
	ds_read_b128 v[6:9], v202 offset:32
	ds_read_b128 v[10:13], v202 offset:64
	ds_read_b128 v[222:225], v202 offset:96
	ds_read_b128 v[226:229], v202 offset:4608
	v_mfma_f32_32x32x8_bf16 v[96:111], v[206:207], v[214:215], 0
	v_mfma_f32_32x32x8_bf16 v[80:95], v[206:207], v[216:217], 0
	s_waitcnt lgkmcnt(4)
	v_mfma_f32_32x32x16_bf16 v[96:111], v[2:5], v[120:123], v[96:111]
	ds_read_b128 v[2:5], v202 offset:4640
	s_waitcnt lgkmcnt(4)
	v_mfma_f32_32x32x16_bf16 v[96:111], v[6:9], v[112:115], v[96:111]
	ds_read_b128 v[6:9], v202 offset:4672
	s_waitcnt lgkmcnt(4)
	v_mfma_f32_32x32x16_bf16 v[96:111], v[10:13], v[116:119], v[96:111]
	ds_read_b128 v[10:13], v202 offset:4704
	s_waitcnt lgkmcnt(4)
	v_mfma_f32_32x32x16_bf16 v[96:111], v[222:225], v[124:127], v[96:111]
	s_waitcnt lgkmcnt(3)
	v_mfma_f32_32x32x16_bf16 v[80:95], v[226:229], v[120:123], v[80:95]
	s_waitcnt lgkmcnt(2)
	v_mfma_f32_32x32x16_bf16 v[80:95], v[2:5], v[112:115], v[80:95]
	s_waitcnt lgkmcnt(1)
	v_mfma_f32_32x32x16_bf16 v[80:95], v[6:9], v[116:119], v[80:95]
	s_waitcnt lgkmcnt(0)
	v_mfma_f32_32x32x16_bf16 v[80:95], v[10:13], v[124:127], v[80:95]
	v_add_u32_e32 v161, 0x4800, v201
	v_add_u32_e32 v173, 0x5800, v201
	v_add_u32_e32 v188, 0x6800, v201
	v_add_u32_e32 v208, 0x7800, v201
	ds_read2_b64 v[222:225], v208 offset0:192 offset1:194
	ds_read2_b64 v[226:229], v161 offset0:4 offset1:6
	s_lshl_b32 s2, s93, 6
	s_sub_i32 s2, s2, 64
	v_cvt_f32_u32_e32 v14, s2
	v_sub_f32_e32 v14, v187, v14
	v_mul_f32_e32 v14, v189, v14
	ds_read2_b64 v[2:5], v161 offset1:2
	ds_read2_b64 v[6:9], v173 offset0:64 offset1:66
	ds_read2_b64 v[10:13], v188 offset0:128 offset1:130
	v_max3_f32 v0, v96, v97, v98
	v_max3_f32 v15, v80, v81, v82
	v_max3_f32 v0, v0, v99, v100
	v_max3_f32 v15, v15, v83, v84
	v_max3_f32 v0, v0, v101, v102
	v_max3_f32 v15, v15, v85, v86
	v_max3_f32 v0, v0, v103, v104
	v_max3_f32 v15, v15, v87, v88
	v_max3_f32 v0, v0, v105, v106
	v_max3_f32 v15, v15, v89, v90
	v_max3_f32 v0, v0, v107, v108
	v_max3_f32 v15, v15, v91, v92
	v_max3_f32 v0, v0, v109, v110
	v_max3_f32 v15, v15, v93, v94
	v_max_f32_e32 v0, v0, v111
	v_max_f32_e32 v15, v15, v95
	v_max_f32_e32 v0, v0, v15
	v_mov_b32_e32 v15, v0
	s_nop 1
	v_permlane32_swap_b32_e32 v15, v0
	s_nop 1
	v_max_f32_e32 v0, v0, v15
	v_fma_f32 v0, v0, s35, -v14
	v_sub_f32_e32 v15, v0, v204
	v_cmp_lt_f32_e32 vcc, 0x41000000, v15
	s_nop 1
	v_cndmask_b32_e32 v15, v204, v0, vcc
	v_sub_f32_e32 v0, v204, v15
	v_exp_f32_e32 v0, v0
	v_mov_b32_e32 v204, v15
	v_add_f32_e32 v14, v15, v14
	s_cbranch_vccz .Lfa_keep
	v_pk_mul_f32 v[78:79], v[78:79], v[0:1] op_sel_hi:[1,0]
	v_pk_mul_f32 v[76:77], v[76:77], v[0:1] op_sel_hi:[1,0]
	v_pk_mul_f32 v[74:75], v[74:75], v[0:1] op_sel_hi:[1,0]
	v_pk_mul_f32 v[72:73], v[72:73], v[0:1] op_sel_hi:[1,0]
	v_pk_mul_f32 v[70:71], v[70:71], v[0:1] op_sel_hi:[1,0]
	v_pk_mul_f32 v[68:69], v[68:69], v[0:1] op_sel_hi:[1,0]
	v_pk_mul_f32 v[66:67], v[66:67], v[0:1] op_sel_hi:[1,0]
	v_pk_mul_f32 v[64:65], v[64:65], v[0:1] op_sel_hi:[1,0]
	v_pk_mul_f32 v[62:63], v[62:63], v[0:1] op_sel_hi:[1,0]
	v_pk_mul_f32 v[60:61], v[60:61], v[0:1] op_sel_hi:[1,0]
	v_pk_mul_f32 v[58:59], v[58:59], v[0:1] op_sel_hi:[1,0]
	v_pk_mul_f32 v[56:57], v[56:57], v[0:1] op_sel_hi:[1,0]
	v_pk_mul_f32 v[54:55], v[54:55], v[0:1] op_sel_hi:[1,0]
	v_pk_mul_f32 v[52:53], v[52:53], v[0:1] op_sel_hi:[1,0]
	v_pk_mul_f32 v[50:51], v[50:51], v[0:1] op_sel_hi:[1,0]
	v_pk_mul_f32 v[48:49], v[48:49], v[0:1] op_sel_hi:[1,0]
	v_pk_mul_f32 v[46:47], v[46:47], v[0:1] op_sel_hi:[1,0]
	v_pk_mul_f32 v[44:45], v[44:45], v[0:1] op_sel_hi:[1,0]
	v_pk_mul_f32 v[42:43], v[42:43], v[0:1] op_sel_hi:[1,0]
	v_pk_mul_f32 v[40:41], v[40:41], v[0:1] op_sel_hi:[1,0]
	v_pk_mul_f32 v[38:39], v[38:39], v[0:1] op_sel_hi:[1,0]
	v_pk_mul_f32 v[36:37], v[36:37], v[0:1] op_sel_hi:[1,0]
	v_pk_mul_f32 v[34:35], v[34:35], v[0:1] op_sel_hi:[1,0]
	v_pk_mul_f32 v[32:33], v[32:33], v[0:1] op_sel_hi:[1,0]
	v_pk_mul_f32 v[30:31], v[30:31], v[0:1] op_sel_hi:[1,0]
	v_pk_mul_f32 v[28:29], v[28:29], v[0:1] op_sel_hi:[1,0]
	v_pk_mul_f32 v[26:27], v[26:27], v[0:1] op_sel_hi:[1,0]
	v_pk_mul_f32 v[24:25], v[24:25], v[0:1] op_sel_hi:[1,0]
	v_pk_mul_f32 v[22:23], v[22:23], v[0:1] op_sel_hi:[1,0]
	v_pk_mul_f32 v[20:21], v[20:21], v[0:1] op_sel_hi:[1,0]
	v_pk_mul_f32 v[18:19], v[18:19], v[0:1] op_sel_hi:[1,0]
	v_pk_mul_f32 v[16:17], v[16:17], v[0:1] op_sel_hi:[1,0]
; DI unsigned pk2(float a, float b) { f32x2 v = {a, b}; bfv2 r = __builtin_convertvector(v, bfv2); return __builtin_bit_cast(unsigned, r); }
; DI void attn_item(const Params& p, int l, int item, char* lds) {
;     ...
;     float ps = 0.f;
; #pragma unroll
;     for (int kt = 0; kt < 2; ++kt)
; #pragma unroll
;       for (int e = 0; e < 16; ++e) { const float pe = __builtin_amdgcn_exp2f(s[kt][e] - mnew); s[kt][e] = pe; ps += pe; }
;     lrun = lrun * alpha + ps;
;     if (__any(resc)) {
; #pragma unroll
;       for (int i = 0; i < 4; ++i)
; #pragma unroll
;         for (int e = 0; e < 16; ++e) O[i][e] *= alpha;
;     }
; #pragma unroll
;     for (int kt = 0; kt < 2; ++kt)
; #pragma unroll
;       for (int sx = 0; sx < 2; ++sx) {
;         u32x4 pb;
;         pb[0] = pk2(s[kt][8 * sx + 0], s[kt][8 * sx + 1]); pb[1] = pk2(s[kt][8 * sx + 2], s[kt][8 * sx + 3]);
;         pb[2] = pk2(s[kt][8 * sx + 4], s[kt][8 * sx + 5]); pb[3] = pk2(s[kt][8 * sx + 6], s[kt][8 * sx + 7]);
;         const bf16x8 pf = __builtin_bit_cast(bf16x8, pb);
; #pragma unroll
;         for (int vt = 0; vt < 4; ++vt) {
;           const bf16_t* vp = Vs + (vt * 32 + q) * ALD + kt * 32 + 16 * sx + 4 * hh;
;           const s16x4 lo = *(const s16x4*)vp, hi = *(const s16x4*)(vp + 8);
;           const bf16x8 vf = __builtin_shufflevector(lo, hi, 0, 1, 2, 3, 4, 5, 6, 7);
;           O[vt] = __builtin_amdgcn_mfma_f32_32x32x16_bf16(vf, pf, O[vt], 0, 0, 0);
;         }
;       }
;     __syncthreads();
;     if (j + 1 < nch) sstore();
.Lfa_keep:
	v_fma_f32 v96, v96, s35, -v14
	v_fma_f32 v97, v97, s35, -v14
	v_fma_f32 v98, v98, s35, -v14
	v_fma_f32 v99, v99, s35, -v14
	v_fma_f32 v100, v100, s35, -v14
	v_fma_f32 v101, v101, s35, -v14
	v_fma_f32 v102, v102, s35, -v14
	v_fma_f32 v103, v103, s35, -v14
	v_exp_f32_e32 v96, v96
	v_exp_f32_e32 v97, v97
	v_exp_f32_e32 v98, v98
	v_exp_f32_e32 v99, v99
	v_exp_f32_e32 v100, v100
	v_exp_f32_e32 v101, v101
	v_exp_f32_e32 v102, v102
	v_exp_f32_e32 v103, v103
	v_add_f32_e32 v15, v96, v98
	v_add_f32_e32 v205, v97, v99
	v_add_f32_e32 v15, v15, v100
	v_add_f32_e32 v205, v205, v101
	v_add_f32_e32 v15, v15, v102
	v_add_f32_e32 v205, v205, v103
	v_cvt_pk_bf16_f32 v96, v96, v97
	v_cvt_pk_bf16_f32 v97, v98, v99
	v_cvt_pk_bf16_f32 v98, v100, v101
	v_cvt_pk_bf16_f32 v99, v102, v103
	v_fma_f32 v104, v104, s35, -v14
	v_fma_f32 v105, v105, s35, -v14
	s_waitcnt lgkmcnt(2)
	v_mfma_f32_32x32x16_bf16 v[64:79], v[2:5], v[96:99], v[64:79]
	ds_read2_b64 v[2:5], v173 offset0:68 offset1:70
	v_fma_f32 v106, v106, s35, -v14
	v_fma_f32 v107, v107, s35, -v14
	v_fma_f32 v108, v108, s35, -v14
	v_fma_f32 v109, v109, s35, -v14
	v_fma_f32 v110, v110, s35, -v14
	v_fma_f32 v111, v111, s35, -v14
	v_exp_f32_e32 v104, v104
	s_waitcnt lgkmcnt(2)
	v_mfma_f32_32x32x16_bf16 v[48:63], v[6:9], v[96:99], v[48:63]
	ds_read2_b64 v[6:9], v188 offset0:132 offset1:134
	v_exp_f32_e32 v105, v105
	v_exp_f32_e32 v106, v106
	v_exp_f32_e32 v107, v107
	v_exp_f32_e32 v108, v108
	v_exp_f32_e32 v109, v109
	v_exp_f32_e32 v110, v110
	v_exp_f32_e32 v111, v111
	s_waitcnt lgkmcnt(2)
	v_mfma_f32_32x32x16_bf16 v[32:47], v[10:13], v[96:99], v[32:47]
	ds_read2_b64 v[10:13], v208 offset0:196 offset1:198
	v_add_f32_e32 v15, v15, v104
	v_add_f32_e32 v205, v205, v105
	v_add_f32_e32 v15, v15, v106
	v_add_f32_e32 v205, v205, v107
	v_add_f32_e32 v15, v15, v108
	v_add_f32_e32 v205, v205, v109
	v_add_f32_e32 v15, v15, v110
	s_waitcnt lgkmcnt(7)
	v_mfma_f32_32x32x16_bf16 v[16:31], v[222:225], v[96:99], v[16:31]
	ds_read2_b64 v[222:225], v161 offset0:8 offset1:10
	v_add_f32_e32 v205, v205, v111
	v_cvt_pk_bf16_f32 v104, v104, v105
	v_cvt_pk_bf16_f32 v105, v106, v107
	v_cvt_pk_bf16_f32 v106, v108, v109
	v_cvt_pk_bf16_f32 v107, v110, v111
	v_fma_f32 v80, v80, s35, -v14
	v_fma_f32 v81, v81, s35, -v14
	s_waitcnt lgkmcnt(7)
	v_mfma_f32_32x32x16_bf16 v[64:79], v[226:229], v[104:107], v[64:79]
	ds_read2_b64 v[226:229], v173 offset0:72 offset1:74
	v_fma_f32 v82, v82, s35, -v14
	v_fma_f32 v83, v83, s35, -v14
	v_fma_f32 v84, v84, s35, -v14
	v_fma_f32 v85, v85, s35, -v14
	v_fma_f32 v86, v86, s35, -v14
	v_fma_f32 v87, v87, s35, -v14
	v_exp_f32_e32 v80, v80
	s_waitcnt lgkmcnt(4)
	v_mfma_f32_32x32x16_bf16 v[48:63], v[2:5], v[104:107], v[48:63]
	ds_read2_b64 v[2:5], v188 offset0:136 offset1:138
	v_exp_f32_e32 v81, v81
	v_exp_f32_e32 v82, v82
	v_exp_f32_e32 v83, v83
	v_exp_f32_e32 v84, v84
	v_exp_f32_e32 v85, v85
	v_exp_f32_e32 v86, v86
	v_exp_f32_e32 v87, v87
	s_waitcnt lgkmcnt(4)
	v_mfma_f32_32x32x16_bf16 v[32:47], v[6:9], v[104:107], v[32:47]
	ds_read2_b64 v[6:9], v208 offset0:200 offset1:202
	v_add_f32_e32 v15, v15, v80
	v_add_f32_e32 v205, v205, v81
	v_add_f32_e32 v15, v15, v82
	v_add_f32_e32 v205, v205, v83
	v_add_f32_e32 v15, v15, v84
	v_add_f32_e32 v205, v205, v85
	v_add_f32_e32 v15, v15, v86
	s_waitcnt lgkmcnt(4)
	v_mfma_f32_32x32x16_bf16 v[16:31], v[10:13], v[104:107], v[16:31]
	ds_read2_b64 v[10:13], v161 offset0:12 offset1:14
	v_add_f32_e32 v205, v205, v87
	v_cvt_pk_bf16_f32 v80, v80, v81
	v_cvt_pk_bf16_f32 v81, v82, v83
	v_cvt_pk_bf16_f32 v82, v84, v85
	v_cvt_pk_bf16_f32 v83, v86, v87
	v_fma_f32 v88, v88, s35, -v14
	v_fma_f32 v89, v89, s35, -v14
	s_waitcnt lgkmcnt(4)
	v_mfma_f32_32x32x16_bf16 v[64:79], v[222:225], v[80:83], v[64:79]
	ds_read2_b64 v[222:225], v173 offset0:76 offset1:78
	v_fma_f32 v90, v90, s35, -v14
	v_fma_f32 v91, v91, s35, -v14
	v_fma_f32 v92, v92, s35, -v14
	v_fma_f32 v93, v93, s35, -v14
	v_fma_f32 v94, v94, s35, -v14
	v_fma_f32 v95, v95, s35, -v14
	v_exp_f32_e32 v88, v88
	s_waitcnt lgkmcnt(4)
	v_mfma_f32_32x32x16_bf16 v[48:63], v[226:229], v[80:83], v[48:63]
	ds_read2_b64 v[226:229], v188 offset0:140 offset1:142
	v_exp_f32_e32 v89, v89
	v_exp_f32_e32 v90, v90
	v_exp_f32_e32 v91, v91
	v_exp_f32_e32 v92, v92
	v_exp_f32_e32 v93, v93
	v_exp_f32_e32 v94, v94
	v_exp_f32_e32 v95, v95
	s_waitcnt lgkmcnt(4)
	v_mfma_f32_32x32x16_bf16 v[32:47], v[2:5], v[80:83], v[32:47]
	ds_read2_b64 v[2:5], v208 offset0:204 offset1:206
	v_add_f32_e32 v15, v15, v88
	v_add_f32_e32 v205, v205, v89
	v_add_f32_e32 v15, v15, v90
	v_add_f32_e32 v205, v205, v91
	v_add_f32_e32 v15, v15, v92
	v_add_f32_e32 v205, v205, v93
	v_add_f32_e32 v15, v15, v94
	s_waitcnt lgkmcnt(4)
	v_mfma_f32_32x32x16_bf16 v[16:31], v[6:9], v[80:83], v[16:31]
	v_add_f32_e32 v205, v205, v95
	v_cvt_pk_bf16_f32 v88, v88, v89
	v_cvt_pk_bf16_f32 v89, v90, v91
	v_cvt_pk_bf16_f32 v90, v92, v93
	v_cvt_pk_bf16_f32 v91, v94, v95
	s_waitcnt lgkmcnt(0)
	s_barrier
	s_nop 1
	v_mfma_f32_32x32x16_bf16 v[64:79], v[10:13], v[88:91], v[64:79]
	s_waitcnt vmcnt(7)
	ds_write_b128 v180, v[128:131]
	s_waitcnt vmcnt(6)
	ds_write_b128 v180, v[132:135] offset:18432
	v_mfma_f32_32x32x16_bf16 v[48:63], v[222:225], v[88:91], v[48:63]
	s_waitcnt vmcnt(5)
	ds_write_b128 v182, v[136:139]
	s_waitcnt vmcnt(4)
	ds_write_b128 v182, v[140:143] offset:18432
	v_mfma_f32_32x32x16_bf16 v[32:47], v[226:229], v[88:91], v[32:47]
	s_waitcnt vmcnt(3)
	ds_write_b128 v184, v[144:147]
	s_waitcnt vmcnt(2)
	ds_write_b128 v184, v[148:151] offset:18432
	v_mfma_f32_32x32x16_bf16 v[16:31], v[2:5], v[88:91], v[16:31]
	s_waitcnt vmcnt(1)
	ds_write_b128 v186, v[152:155]
	s_waitcnt vmcnt(0)
	ds_write_b128 v186, v[156:159] offset:18432
	v_add_f32_e32 v15, v15, v205
	s_add_u32 s36, s36, 0x80
	s_addc_u32 s37, s37, 0
	s_add_i32 s38, s38, 64
	s_add_i32 s92, s92, 64
	v_fma_f32 v203, v203, v0, v15
	v_add_u32_e32 v199, 64, v199
	s_mov_b32 s39, s93
	s_branch .LBB0_591
; DI void attn_item(const Params& p, int l, int item, char* lds) {
;     ...
;   for (int j = 0; j < nch; ++j) {
;     if (j + 1 < nch) gload(j + 1);
;     f32x16 s[2];
; #pragma unroll
;     for (int kt = 0; kt < 2; ++kt) {
; #pragma unroll
;       for (int e = 0; e < 16; ++e) s[kt][e] = 0.f;
; #pragma unroll
;       for (int ks = 0; ks < 4; ++ks) {
;         const bf16x8 kf = *(const bf16x8*)(Ks + (m * 64 + kt * 32 + q) * ALD + ks * 16 + hh * 8);
;         s[kt] = __builtin_amdgcn_mfma_f32_32x32x16_bf16(kf, qf[ks], s[kt], 0, 0, 0);
;       }
;     }
;     float mx = -1e30f;
;     const float dbase = qposf - (float)(j * 64 + 4 * hh);
; #pragma unroll
;     for (int kt = 0; kt < 2; ++kt)
; #pragma unroll
;       for (int e = 0; e < 16; ++e) {
;         const float dd = dbase - (float)(kt * 32 + (e & 3) + 8 * (e >> 2));
;         const float v = s[kt][e] * c1 - sl2 * fabsf(dd);
;         s[kt][e] = v; mx = fmaxf(mx, v);
;       }
;     mx = fmaxf(mx, __shfl_xor(mx, 32));
;     const float mnew = fmaxf(mrun, mx);
;     const float alpha = __builtin_amdgcn_exp2f(mrun - mnew);
;     const bool resc = mnew > mrun;
;     mrun = mnew;
;     float ps = 0.f;
; #pragma unroll
;     for (int kt = 0; kt < 2; ++kt)
; #pragma unroll
;       for (int e = 0; e < 16; ++e) { const float pe = __builtin_amdgcn_exp2f(s[kt][e] - mnew); s[kt][e] = pe; ps += pe; }
;     lrun = lrun * alpha + ps;
;     if (__any(resc)) {
; #pragma unroll
;       for (int i = 0; i < 4; ++i)
; #pragma unroll
;         for (int e = 0; e < 16; ++e) O[i][e] *= alpha;
.LBB0_600:
	s_waitcnt lgkmcnt(0)
	s_barrier
	ds_read_b128 v[2:5], v202
	ds_read_b128 v[6:9], v202 offset:32
	ds_read_b128 v[10:13], v202 offset:64
	ds_read_b128 v[214:217], v202 offset:96
	ds_read_b128 v[222:225], v202 offset:4608
	ds_read_b128 v[226:229], v202 offset:4640
	v_cvt_f32_u32_e32 v0, v199
	s_mov_b32 s2, 0xf149f2ca
	v_sub_f32_e32 v0, v187, v0
	s_waitcnt lgkmcnt(5)
	v_mfma_f32_32x32x16_bf16 v[96:111], v[2:5], v[120:123], 0
	ds_read_b128 v[2:5], v202 offset:4672
	s_waitcnt lgkmcnt(5)
	v_mfma_f32_32x32x16_bf16 v[96:111], v[6:9], v[112:115], v[96:111]
	ds_read_b128 v[6:9], v202 offset:4704
	s_waitcnt lgkmcnt(5)
	v_mfma_f32_32x32x16_bf16 v[96:111], v[10:13], v[116:119], v[96:111]
	s_waitcnt lgkmcnt(4)
	v_mfma_f32_32x32x16_bf16 v[96:111], v[214:217], v[124:127], v[96:111]
	s_waitcnt lgkmcnt(3)
	v_mfma_f32_32x32x16_bf16 v[80:95], v[222:225], v[120:123], 0
	s_waitcnt lgkmcnt(2)
	v_mfma_f32_32x32x16_bf16 v[80:95], v[226:229], v[112:115], v[80:95]
	s_waitcnt lgkmcnt(1)
	v_mfma_f32_32x32x16_bf16 v[80:95], v[2:5], v[116:119], v[80:95]
	s_waitcnt lgkmcnt(0)
	v_mfma_f32_32x32x16_bf16 v[80:95], v[6:9], v[124:127], v[80:95]
	v_add_f32_e32 v11, 0xc2640000, v0
	v_add_f32_e32 v9, 0xc24c0000, v0
	v_add_f32_e32 v5, -2.0, v0
	v_mul_f32_e64 v2, v189, |v0|
	v_mul_f32_e64 v5, v189, |v5|
	v_fma_f32 v3, v96, s35, -v2
	v_fma_f32 v96, v98, s35, -v5
	v_add_f32_e32 v5, 0xc0400000, v0
	v_mul_f32_e64 v5, v189, |v5|
	v_fma_f32 v173, v99, s35, -v5
	v_add_f32_e32 v5, 0xc1000000, v0
	v_mul_f32_e64 v5, v189, |v5|
	v_fma_f32 v205, v100, s35, -v5
	v_add_f32_e32 v5, 0xc1100000, v0
	v_mul_f32_e64 v5, v189, |v5|
	v_fma_f32 v206, v101, s35, -v5
	v_add_f32_e32 v5, 0xc1200000, v0
	v_mul_f32_e64 v5, v189, |v5|
	v_fma_f32 v10, v102, s35, -v5
	v_add_f32_e32 v5, 0xc1300000, v0
	v_mul_f32_e64 v5, v189, |v5|
	v_fma_f32 v13, v103, s35, -v5
	v_add_f32_e32 v5, 0xc1800000, v0
	v_mul_f32_e64 v5, v189, |v5|
	v_fma_f32 v15, v104, s35, -v5
	v_add_f32_e32 v5, 0xc1880000, v0
	v_mul_f32_e64 v5, v189, |v5|
	v_fma_f32 v103, v105, s35, -v5
	v_add_f32_e32 v5, 0xc1900000, v0
	v_mul_f32_e64 v5, v189, |v5|
	v_fma_f32 v105, v106, s35, -v5
	v_add_f32_e32 v5, 0xc1980000, v0
	v_mul_f32_e64 v5, v189, |v5|
	v_fma_f32 v107, v107, s35, -v5
	v_add_f32_e32 v5, 0xc1c00000, v0
	v_mul_f32_e64 v5, v189, |v5|
	v_fma_f32 v102, v108, s35, -v5
	v_add_f32_e32 v5, 0xc1c80000, v0
	v_mul_f32_e64 v5, v189, |v5|
	v_fma_f32 v104, v109, s35, -v5
	v_add_f32_e32 v5, 0xc1d00000, v0
	v_mul_f32_e64 v5, v189, |v5|
	v_fma_f32 v106, v110, s35, -v5
	v_add_f32_e32 v5, 0xc1d80000, v0
	v_mul_f32_e64 v5, v189, |v5|
	v_fma_f32 v101, v111, s35, -v5
	v_add_f32_e32 v5, 0xc2000000, v0
	v_mul_f32_e64 v5, v189, |v5|
	v_add_f32_e32 v2, -1.0, v0
	v_fma_f32 v100, v80, s35, -v5
	v_add_f32_e32 v5, 0xc2040000, v0
	v_mul_f32_e64 v2, v189, |v2|
	v_mul_f32_e64 v5, v189, |v5|
	v_fma_f32 v4, v97, s35, -v2
	v_fma_f32 v97, v81, s35, -v5
	v_add_f32_e32 v5, 0xc2080000, v0
	v_mul_f32_e64 v5, v189, |v5|
	v_fma_f32 v98, v82, s35, -v5
	v_add_f32_e32 v5, 0xc20c0000, v0
	v_mul_f32_e64 v5, v189, |v5|
	v_fma_f32 v99, v83, s35, -v5
	v_add_f32_e32 v5, 0xc2200000, v0
	v_mul_f32_e64 v5, v189, |v5|
	v_fma_f32 v80, v84, s35, -v5
	v_add_f32_e32 v5, 0xc2240000, v0
	v_mul_f32_e64 v5, v189, |v5|
	v_max3_f32 v2, v3, s2, v4
	v_fma_f32 v81, v85, s35, -v5
	v_add_f32_e32 v5, 0xc2280000, v0
	v_max3_f32 v2, v2, v96, v173
	v_mul_f32_e64 v5, v189, |v5|
	v_max3_f32 v2, v2, v205, v206
	v_fma_f32 v82, v86, s35, -v5
	v_add_f32_e32 v5, 0xc22c0000, v0
	v_max3_f32 v2, v2, v10, v13
	v_and_b32_e32 v161, 0x7fffffff, v5
	v_mov_b32_e32 v188, v87
	v_add_f32_e32 v5, 0xc2400000, v0
	v_max3_f32 v2, v2, v15, v103
	v_pk_mul_f32 v[6:7], v[188:189], v[160:161]
	v_and_b32_e32 v161, 0x7fffffff, v5
	v_mov_b32_e32 v188, v88
	v_max3_f32 v2, v2, v105, v107
	v_sub_f32_e32 v8, v6, v7
	v_pk_mul_f32 v[6:7], v[188:189], v[160:161]
	v_add_f32_e32 v5, 0xc2440000, v0
	v_max3_f32 v2, v2, v102, v104
	v_sub_f32_e32 v6, v6, v7
	v_and_b32_e32 v161, 0x7fffffff, v5
	v_mov_b32_e32 v188, v89
	v_add_f32_e32 v7, 0xc2480000, v0
	v_max3_f32 v2, v2, v106, v101
	v_pk_mul_f32 v[84:85], v[188:189], v[160:161]
	v_and_b32_e32 v161, 0x7fffffff, v7
	v_mov_b32_e32 v188, v90
	v_max3_f32 v2, v2, v100, v97
	v_sub_f32_e32 v5, v84, v85
	v_pk_mul_f32 v[84:85], v[188:189], v[160:161]
	v_and_b32_e32 v161, 0x7fffffff, v9
	v_mov_b32_e32 v188, v91
	v_add_f32_e32 v9, 0xc2600000, v0
	v_max3_f32 v2, v2, v98, v99
	v_sub_f32_e32 v7, v84, v85
	v_pk_mul_f32 v[84:85], v[188:189], v[160:161]
	v_and_b32_e32 v161, 0x7fffffff, v9
	v_mov_b32_e32 v188, v92
	v_max3_f32 v2, v2, v80, v81
	v_sub_f32_e32 v12, v84, v85
	v_pk_mul_f32 v[84:85], v[188:189], v[160:161]
	v_and_b32_e32 v161, 0x7fffffff, v11
	v_mov_b32_e32 v188, v93
	v_add_f32_e32 v11, 0xc2680000, v0
	v_max3_f32 v2, v2, v82, v8
	v_sub_f32_e32 v9, v84, v85
	v_pk_mul_f32 v[84:85], v[188:189], v[160:161]
	v_and_b32_e32 v161, 0x7fffffff, v11
	v_mov_b32_e32 v188, v94
	v_add_f32_e32 v0, 0xc26c0000, v0
	v_max3_f32 v2, v2, v6, v5
	v_sub_f32_e32 v14, v84, v85
	v_pk_mul_f32 v[84:85], v[188:189], v[160:161]
	v_and_b32_e32 v161, 0x7fffffff, v0
	v_mov_b32_e32 v188, v95
	v_max3_f32 v2, v2, v7, v12
	v_sub_f32_e32 v83, v84, v85
	v_pk_mul_f32 v[84:85], v[188:189], v[160:161]
	v_max3_f32 v2, v2, v9, v14
	v_sub_f32_e32 v11, v84, v85
	v_max3_f32 v0, v2, v83, v11
	ds_bpermute_b32 v2, v200, v0
	s_waitcnt lgkmcnt(0)
	v_max_f32_e32 v2, v0, v2
	v_sub_f32_e32 v0, v2, v204
	v_cmp_lt_f32_e32 vcc, 0x41000000, v0
	s_nop 1
	v_cndmask_b32_e32 v2, v204, v2, vcc
	v_sub_f32_e32 v0, v204, v2
	v_exp_f32_e32 v0, v0
	s_cbranch_vccz .LBB0_602
; DI void attn_item(const Params& p, int l, int item, char* lds) {
;     ...
;     if (__any(resc)) {
; #pragma unroll
;       for (int i = 0; i < 4; ++i)
; #pragma unroll
;         for (int e = 0; e < 16; ++e) O[i][e] *= alpha;
;     }
	v_pk_mul_f32 v[78:79], v[78:79], v[0:1] op_sel_hi:[1,0]
	v_pk_mul_f32 v[76:77], v[76:77], v[0:1] op_sel_hi:[1,0]
	v_pk_mul_f32 v[74:75], v[74:75], v[0:1] op_sel_hi:[1,0]
	v_pk_mul_f32 v[72:73], v[72:73], v[0:1] op_sel_hi:[1,0]
	v_pk_mul_f32 v[70:71], v[70:71], v[0:1] op_sel_hi:[1,0]
	v_pk_mul_f32 v[68:69], v[68:69], v[0:1] op_sel_hi:[1,0]
	v_pk_mul_f32 v[66:67], v[66:67], v[0:1] op_sel_hi:[1,0]
	v_pk_mul_f32 v[64:65], v[64:65], v[0:1] op_sel_hi:[1,0]
	v_pk_mul_f32 v[62:63], v[62:63], v[0:1] op_sel_hi:[1,0]
	v_pk_mul_f32 v[60:61], v[60:61], v[0:1] op_sel_hi:[1,0]
	v_pk_mul_f32 v[58:59], v[58:59], v[0:1] op_sel_hi:[1,0]
	v_pk_mul_f32 v[56:57], v[56:57], v[0:1] op_sel_hi:[1,0]
	v_pk_mul_f32 v[54:55], v[54:55], v[0:1] op_sel_hi:[1,0]
	v_pk_mul_f32 v[52:53], v[52:53], v[0:1] op_sel_hi:[1,0]
	v_pk_mul_f32 v[50:51], v[50:51], v[0:1] op_sel_hi:[1,0]
	v_pk_mul_f32 v[48:49], v[48:49], v[0:1] op_sel_hi:[1,0]
	v_pk_mul_f32 v[46:47], v[46:47], v[0:1] op_sel_hi:[1,0]
	v_pk_mul_f32 v[44:45], v[44:45], v[0:1] op_sel_hi:[1,0]
	v_pk_mul_f32 v[42:43], v[42:43], v[0:1] op_sel_hi:[1,0]
	v_pk_mul_f32 v[40:41], v[40:41], v[0:1] op_sel_hi:[1,0]
	v_pk_mul_f32 v[38:39], v[38:39], v[0:1] op_sel_hi:[1,0]
	v_pk_mul_f32 v[36:37], v[36:37], v[0:1] op_sel_hi:[1,0]
	v_pk_mul_f32 v[34:35], v[34:35], v[0:1] op_sel_hi:[1,0]
	v_pk_mul_f32 v[32:33], v[32:33], v[0:1] op_sel_hi:[1,0]
	v_pk_mul_f32 v[30:31], v[30:31], v[0:1] op_sel_hi:[1,0]
	v_pk_mul_f32 v[28:29], v[28:29], v[0:1] op_sel_hi:[1,0]
	v_pk_mul_f32 v[26:27], v[26:27], v[0:1] op_sel_hi:[1,0]
	v_pk_mul_f32 v[24:25], v[24:25], v[0:1] op_sel_hi:[1,0]
	v_pk_mul_f32 v[22:23], v[22:23], v[0:1] op_sel_hi:[1,0]
	v_pk_mul_f32 v[20:21], v[20:21], v[0:1] op_sel_hi:[1,0]
	v_pk_mul_f32 v[18:19], v[18:19], v[0:1] op_sel_hi:[1,0]
	v_pk_mul_f32 v[16:17], v[16:17], v[0:1] op_sel_hi:[1,0]
